# v060 plus FoX prologue: carr loads issued with the CTL norm loads, min-tid waterfall loop replaced by first-active-lane readlane; masked tiles: compare/select pairs issued three at a time via spare SG
# speedup vs baseline: 1.0056x; 1.0008x over previous
; DI void fox_unit(const Params& P, lptr L, int u, int tid, int lane, int wid) {
;     ...
;     const int bh = u & 15, b = bh >> 3, h = bh & 7, qt = 63 - (u >> 4);
;     const int i = lane & 31, hi = lane >> 5;
; __global__ void __launch_bounds__(512) fwd_kernel(Params P) {
;     ...
;             __syncthreads();
;             if (tid == 0) qs_[0] = (int)atomicAdd(CTL + CW_Q3 + REPQ, 1u);
;             __syncthreads();
;             const int u = qs_[0];
;             const int nlate = transposes_total(true), nlate_wg = (nlate + 7) >> 3;
;             if (u >= 128 + 2048 + nlate_wg) break;
;             if (u >= 128 + 2048) {
;                 const int idx = (u - (128 + 2048)) * 8 + wid;
;                 if (idx < nlate) transpose_by_index(P, ws, (LAS float*)(L + 40960 + wid * 8448), idx, true, lane);
;                 continue;
;             }
;             if (u < 128) {
;                 const int which = u >> 6; const float* w2 = P.cmp_w2 + which * 4096;
;                 float wcol[64];
; #pragma unroll
;                 for (int i2 = 0; i2 < 64; ++i2) wcol[i2] = w2[i2 * 64 + lane];
;                 const float* HIDP = (const float*)(ws + WS_HIDP); bf16_t* KC = (bf16_t*)(ws + WS_KC); bf16_t* VCT = (bf16_t*)(ws + WS_VCT);
;                 const float cb = ((const float*)(ws + WS_CBIAS))[which * 64 + lane];
;                 for (int rr = 0; rr < 8; ++rr) { const int ridx = u * 64 + wid * 8 + rr; const int n = ridx & 1023, bgi = (ridx >> 10) & 3;
;                     float hs = cb;
; #pragma unroll
;                     for (int ks = 0; ks < 8; ++ks) hs += HIDP[((size_t)ks * 8192 + ridx) * 64 + lane];
;                     const float hv = pg8::gelu_tanh_f(hs); float o = 0.f;
; #pragma unroll
;                     for (int i2 = 0; i2 < 64; ++i2) o += __shfl(hv, i2) * wcol[i2];
;                     if (n == 1023) o = 0.f;
;                     const bf16_t ob = (bf16_t)(pk_bf16(o, 0.f) & 0xffffu);
;                     if (which == 0) KC[((size_t)bgi * 1024 + n) * 64 + lane] = ob; else VCT[((size_t)bgi * 64 + lane) * 1024 + n] = ob; }
;                 asm volatile("s_waitcnt vmcnt(0)" ::: "memory");
;                 __syncthreads();
;                 if (tid == 0) { __threadfence(); atomicAdd(CTL + CW_PPDONE + REPQ, 1u); }
;             } else {
;                 const int v = u - 128;
;                 if (v & 1) fox_unit(P, L, v >> 1, tid, lane, wid);
.LBB0_472:
	s_or_b64 exec, exec, s[0:1]
	s_waitcnt lgkmcnt(0)
	s_barrier
	ds_read_b32 v0, v1 offset:37632
	v_readlane_b32 s0, v250, 29
	v_readlane_b32 s1, v250, 30
	s_xor_b64 s[24:25], s[0:1], -1
	v_readlane_b32 s0, v251, 57
	s_waitcnt lgkmcnt(0)
	v_readfirstlane_b32 s7, v0
	v_cmp_le_i32_e64 s[20:21], s0, v0
	s_and_b64 vcc, exec, s[20:21]
	s_cbranch_vccnz .LBB0_467
	s_cmpk_lt_i32 s7, 0x880
	s_mov_b64 s[2:3], -1
	s_cbranch_scc0 .LBB0_634
	s_cmpk_gt_i32 s7, 0x7f
	s_cbranch_scc0 .LBB0_626
	s_add_i32 s47, s7, 0xffffff80
	s_bitcmp0_b32 s7, 0
	s_mov_b64 s[0:1], -1
	s_cbranch_scc1 .LBB0_518
	s_lshr_b32 s0, s47, 5
	s_xor_b32 s3, s0, 63
	s_lshl_b32 s53, s3, 2
	s_mov_b64 s[0:1], exec
	v_readlane_b32 s22, v251, 20
	v_readlane_b32 s23, v251, 21
	s_and_b64 s[22:23], s[0:1], s[22:23]
	s_mov_b64 exec, s[22:23]
	v_mov_b32_e32 v0, s53
	ds_write_b32 v1, v0 offset:37376
	s_or_b64 exec, exec, s[0:1]
	s_lshl_b32 s0, s47, 15
	s_bfe_u32 s2, s7, 0x10004
	s_bfe_u32 s33, s47, 0x30001
	s_lshl_b32 s22, s3, 8
	s_and_b32 s0, s0, 0xf0000
	v_readlane_b32 s1, v251, 62
	s_add_u32 s26, s1, s0
	v_readlane_b32 s0, v251, 63
	s_addc_u32 s27, s0, 0
	v_cmp_gt_u32_e32 vcc, s53, v194
	s_waitcnt lgkmcnt(0)
	s_barrier
	s_and_saveexec_b64 s[28:29], vcc
	s_cbranch_execz .LBB0_484
	s_lshl_b32 s0, s33, 2
	s_lshl_b32 s1, s2, 6
	s_or_b32 s0, s1, s0
	v_mov_b32_e32 v0, s0
	global_load_dword v2, v0, s[34:35] offset:768
	s_mov_b32 s23, s83
	global_load_dword v0, v0, s[34:35] offset:800
	s_lshl_b64 s[0:1], s[22:23], 2
	s_add_u32 s0, s26, s0
	s_addc_u32 s1, s27, s1
	global_load_dword v6, v1, s[0:1]
	global_load_dword v7, v203, s[26:27] offset:252
	s_mov_b32 s0, 0xf800000
	s_waitcnt vmcnt(0)
	v_mul_f32_e32 v0, v2, v0
	v_cmp_gt_f32_e32 vcc, s0, v0
	v_mul_f32_e32 v2, 0x4f800000, v0
	s_nop 0
	v_cndmask_b32_e32 v0, v0, v2, vcc
	v_sqrt_f32_e32 v2, v0
	s_nop 0
	v_add_u32_e32 v3, -1, v2
	v_fma_f32 v4, -v3, v2, v0
	v_cmp_ge_f32_e64 s[0:1], 0, v4
	v_add_u32_e32 v4, 1, v2
	s_nop 0
	v_cndmask_b32_e64 v3, v2, v3, s[0:1]
	v_fma_f32 v2, -v4, v2, v0
	v_cmp_lt_f32_e64 s[0:1], 0, v2
	s_nop 1
	v_cndmask_b32_e64 v2, v3, v4, s[0:1]
	v_mul_f32_e32 v3, 0x37800000, v2
	v_cndmask_b32_e32 v2, v2, v3, vcc
	v_cmp_class_f32_e32 vcc, v0, v202
	s_mov_b32 s0, 0x3f33385b
	s_nop 0
	v_cndmask_b32_e32 v0, v2, v0, vcc
	v_add_f32_e32 v0, v0, v0
	v_fma_f32 v0, v0, s0, 0.5
	s_mov_b32 s0, 0xc1f00000
	v_sub_f32_e32 v2, v6, v7
	v_add_f32_e32 v0, v2, v0
	v_cmp_le_f32_e32 vcc, s0, v0
	s_and_b64 exec, exec, vcc
	s_cbranch_execz .LBB0_484
	s_ff1_i32_b64 s23, exec
	s_nop 0
	v_readlane_b32 s3, v194, s23
	v_mbcnt_lo_u32_b32 v0, exec_lo, 0
	v_mbcnt_hi_u32_b32 v0, exec_hi, v0
	v_cmp_eq_u32_e32 vcc, 0, v0
	s_and_saveexec_b64 s[0:1], vcc
	s_xor_b64 s[0:1], exec, s[0:1]
	v_mov_b32_e32 v0, s3
	ds_min_i32 v1, v0 offset:37376

; #define LAS __attribute__((address_space(3)))
; #define MFMA32(a, b, c) __builtin_amdgcn_mfma_f32_32x32x16_bf16((a), (b), (c), 0, 0, 0)
; DI void qk_acc(lptr Kt, const bf16x8 (&qf)[4], f32x16& s0, f32x16& s1, int lane) {
;     const int i = lane & 31, hi = lane >> 5;
;     const int krow = (i & 19) | ((i & 4) << 1) | ((i & 8) >> 1);
;     lptr kp = Kt + krow * KPB + hi * 16;
;     bf16x8 a0[4], a1[4];
; #pragma unroll
;     for (int d0 = 0; d0 < 4; ++d0) { a0[d0] = *(LAS bf16x8*)(kp + d0 * 32); a1[d0] = *(LAS bf16x8*)(kp + 32 * KPB + d0 * 32); }
;     __builtin_amdgcn_s_setprio(1);
; #pragma unroll
;     for (int d0 = 0; d0 < 4; ++d0) { s0 = MFMA32(a0[d0], qf[d0], s0); s1 = MFMA32(a1[d0], qf[d0], s1); }
;     __builtin_amdgcn_s_setprio(0);
; template <int MODE>
; DI void bias_init(f32x16& s0, f32x16& s1, const TP& tp, float fbm, int hi) {
; #pragma unroll
;     for (int r = 0; r < 16; ++r) {
;         const int kvc = 16 * (r >> 3) + (r & 7);
;         if (MODE == 0) { s0[r] = __builtin_fmaf(-L2E, tp.cs[kvc + 8 * hi], fbm); s1[r] = __builtin_fmaf(-L2E, tp.cs[kvc + 32 + 8 * hi], fbm); }
;         else { s0[r] = __builtin_fmaf(tp.sl, (float)kvc, fbm); s1[r] = __builtin_fmaf(tp.sl, (float)(kvc + 32), fbm); }
;     }
; }
; DI float max3_asm(float a, float b, float c) { float r; asm("v_max3_f32 %0, %1, %2, %3" : "=v"(r) : "v"(a), "v"(b), "v"(c)); return r; }
; template <bool MASK>
; DI float mask_rowmax(f32x16& s0, f32x16& s1, const TP& tp) {
;     if (MASK) {
; #pragma unroll
;         for (int r = 0; r < 16; ++r) {
;             const int kvc = 16 * (r >> 3) + (r & 7);
;             const bool v0 = tp.sel && (kvc <= tp.lim) && (kvc > tp.lim2), v1 = tp.sel && (kvc + 32 <= tp.lim) && (kvc + 32 > tp.lim2);
;             s0[r] = v0 ? s0[r] : -1e30f; s1[r] = v1 ? s1[r] : -1e30f;
;         }
;     }
;     const float seed = __builtin_fminf(s0[15], s1[15]);
;     float ma = seed, mb = seed;
; #pragma unroll
;     for (int r = 0; r < 16; r += 2) { ma = max3_asm(ma, s0[r], s1[r]); mb = max3_asm(mb, s0[r + 1], s1[r + 1]); }
;     const float mx = fmaxf(ma, mb);
;     return fmaxf(mx, __shfl_xor(mx, 32));
; }
.LBB0_498:
	s_and_b64 vcc, exec, s[2:3]
	s_cbranch_vccz .LBB0_503
	s_nop 8
	ds_read_b128 v[50:53], v162 offset:36992
	ds_read_b128 v[34:37], v162 offset:36864
	ds_read_b128 v[38:41], v162 offset:36880
	ds_read_b128 v[54:57], v162 offset:37008
	ds_read_b128 v[42:45], v162 offset:36928
	ds_read_b128 v[58:61], v162 offset:37056
	ds_read_b128 v[46:49], v162 offset:36944
	ds_read_b128 v[62:65], v162 offset:37072
	ds_read_b128 v[66:69], v161 offset:4608
	ds_read_b128 v[70:73], v161
	ds_read_b128 v[74:77], v161 offset:32
	ds_read_b128 v[78:81], v161 offset:4640
	ds_read_b128 v[82:85], v161 offset:64
	ds_read_b128 v[86:89], v161 offset:4672
	ds_read_b128 v[90:93], v161 offset:96
	ds_read_b128 v[94:97], v161 offset:4704
	s_waitcnt lgkmcnt(11)
	v_pk_fma_f32 v[44:45], v[44:45], s[80:81], v[156:157] op_sel_hi:[1,0,0]
	v_pk_fma_f32 v[40:41], v[40:41], s[80:81], v[156:157] op_sel_hi:[1,0,0]
	v_pk_fma_f32 v[36:37], v[36:37], s[80:81], v[156:157] op_sel_hi:[1,0,0]
	s_waitcnt lgkmcnt(9)
	v_pk_fma_f32 v[46:47], v[46:47], s[80:81], v[156:157] op_sel_hi:[1,0,0]
	v_pk_fma_f32 v[42:43], v[42:43], s[80:81], v[156:157] op_sel_hi:[1,0,0]
	v_pk_fma_f32 v[38:39], v[38:39], s[80:81], v[156:157] op_sel_hi:[1,0,0]
	v_pk_fma_f32 v[34:35], v[34:35], s[80:81], v[156:157] op_sel_hi:[1,0,0]
	v_pk_fma_f32 v[56:57], v[56:57], s[80:81], v[156:157] op_sel_hi:[1,0,0]
	v_pk_fma_f32 v[52:53], v[52:53], s[80:81], v[156:157] op_sel_hi:[1,0,0]
	v_pk_fma_f32 v[54:55], v[54:55], s[80:81], v[156:157] op_sel_hi:[1,0,0]
	v_pk_fma_f32 v[50:51], v[50:51], s[80:81], v[156:157] op_sel_hi:[1,0,0]
	v_pk_fma_f32 v[48:49], v[48:49], s[80:81], v[156:157] op_sel_hi:[1,0,0]
	s_waitcnt lgkmcnt(8)
	v_pk_fma_f32 v[64:65], v[64:65], s[80:81], v[156:157] op_sel_hi:[1,0,0]
	v_pk_fma_f32 v[60:61], v[60:61], s[80:81], v[156:157] op_sel_hi:[1,0,0]
	v_pk_fma_f32 v[62:63], v[62:63], s[80:81], v[156:157] op_sel_hi:[1,0,0]
	v_pk_fma_f32 v[58:59], v[58:59], s[80:81], v[156:157] op_sel_hi:[1,0,0]
	s_setprio 1
	s_waitcnt lgkmcnt(6)
	v_mfma_f32_32x32x16_bf16 v[34:49], v[70:73], v[98:101], v[34:49]
	v_mfma_f32_32x32x16_bf16 v[50:65], v[66:69], v[98:101], v[50:65]
	s_waitcnt lgkmcnt(5)
	v_mfma_f32_32x32x16_bf16 v[34:49], v[74:77], v[102:105], v[34:49]
	s_waitcnt lgkmcnt(4)
	v_mfma_f32_32x32x16_bf16 v[50:65], v[78:81], v[102:105], v[50:65]
	s_waitcnt lgkmcnt(3)
	v_mfma_f32_32x32x16_bf16 v[34:49], v[82:85], v[106:109], v[34:49]
	s_waitcnt lgkmcnt(2)
	v_mfma_f32_32x32x16_bf16 v[50:65], v[86:89], v[106:109], v[50:65]
	s_waitcnt lgkmcnt(1)
	v_mfma_f32_32x32x16_bf16 v[34:49], v[90:93], v[110:113], v[34:49]
	s_waitcnt lgkmcnt(0)
	v_mfma_f32_32x32x16_bf16 v[50:65], v[94:97], v[110:113], v[50:65]
	s_setprio 0
	v_cmp_lt_i32_e32 vcc, 0, v158
	s_mov_b32 s2, 0xefa18f08
	s_nop 6
	v_cndmask_b32_e32 v72, v210, v35, vcc
	v_cmp_lt_i32_e64 s[98:99], -1, v158
	v_cmp_lt_i32_e64 s[100:101], 32, v158
	v_cmp_lt_i32_e32 vcc, 31, v158
	v_cndmask_b32_e64 v76, v210, v34, s[98:99]
	v_cndmask_b32_e64 v66, v210, v51, s[100:101]
	v_cndmask_b32_e32 v68, v210, v50, vcc
	v_cmp_lt_i32_e64 s[98:99], 2, v158
	v_cmp_lt_i32_e64 s[100:101], 1, v158
	v_cmp_lt_i32_e32 vcc, 34, v158
	v_cndmask_b32_e64 v71, v210, v37, s[98:99]
	v_cndmask_b32_e64 v75, v210, v36, s[100:101]
	v_cndmask_b32_e32 v53, v210, v53, vcc
	v_cmp_lt_i32_e64 s[98:99], 33, v158
	v_cmp_lt_i32_e64 s[100:101], 4, v158
	v_cmp_lt_i32_e32 vcc, 3, v158
	v_cndmask_b32_e64 v67, v210, v52, s[98:99]
	v_cndmask_b32_e64 v70, v210, v39, s[100:101]
	v_cndmask_b32_e32 v74, v210, v38, vcc
	v_cmp_lt_i32_e64 s[98:99], 36, v158
	v_cmp_lt_i32_e64 s[100:101], 35, v158
	v_cmp_lt_i32_e32 vcc, 6, v158
	v_cndmask_b32_e64 v51, v210, v55, s[98:99]
	v_cndmask_b32_e64 v54, v210, v54, s[100:101]
	v_cndmask_b32_e32 v69, v210, v41, vcc
	v_cmp_lt_i32_e64 s[98:99], 5, v158
	v_cmp_lt_i32_e64 s[100:101], 38, v158
	v_cmp_lt_i32_e32 vcc, 37, v158
	v_cndmask_b32_e64 v73, v210, v40, s[98:99]
	v_cndmask_b32_e64 v50, v210, v57, s[100:101]
	v_cndmask_b32_e32 v52, v210, v56, vcc
	v_cmp_lt_i32_e64 s[98:99], 16, v158
	v_cmp_lt_i32_e64 s[100:101], 15, v158
	v_cmp_lt_i32_e32 vcc, 48, v158
	v_cndmask_b32_e64 v55, v210, v43, s[98:99]
	v_cndmask_b32_e64 v57, v210, v42, s[100:101]
	v_cndmask_b32_e32 v38, v210, v59, vcc
	v_cmp_lt_i32_e64 s[98:99], 47, v158
	v_cmp_lt_i32_e64 s[100:101], 18, v158
	v_cmp_lt_i32_e32 vcc, 17, v158
	v_cndmask_b32_e64 v41, v210, v58, s[98:99]
	v_cndmask_b32_e64 v45, v210, v45, s[100:101]
	v_cndmask_b32_e32 v56, v210, v44, vcc
	v_cmp_lt_i32_e64 s[98:99], 50, v158
	v_cmp_lt_i32_e64 s[100:101], 49, v158
	v_cmp_lt_i32_e32 vcc, 20, v158
	v_cndmask_b32_e64 v36, v210, v61, s[98:99]
	v_cndmask_b32_e64 v40, v210, v60, s[100:101]
	v_cndmask_b32_e32 v43, v210, v47, vcc
	v_cmp_lt_i32_e64 s[98:99], 19, v158
	v_cmp_lt_i32_e64 s[100:101], 52, v158
	v_cmp_lt_i32_e32 vcc, 51, v158
	v_cndmask_b32_e64 v46, v210, v46, s[98:99]
	v_cndmask_b32_e64 v35, v210, v63, s[100:101]
	v_cndmask_b32_e32 v39, v210, v62, vcc
	v_cmp_lt_i32_e32 vcc, 22, v158
	s_nop 1
	v_cndmask_b32_e32 v42, v210, v49, vcc
	v_cmp_lt_i32_e32 vcc, 21, v158
	v_and_b32_e32 v49, 64, v209
	v_add_u32_e32 v49, 64, v49
	v_cndmask_b32_e32 v44, v210, v48, vcc
	v_cmp_lt_i32_e32 vcc, 54, v158
	v_max_f32_e32 v48, v42, v42
	s_nop 0
	v_cndmask_b32_e32 v34, v210, v65, vcc
	v_max_f32_e32 v47, v34, v34
	v_min_f32_e32 v47, v48, v47
	v_max3_f32 v48, v47, v76, v68
	v_max3_f32 v47, v47, v72, v66
	v_cmp_lt_i32_e32 vcc, 53, v158
	v_max3_f32 v48, v48, v75, v67
	v_max3_f32 v47, v47, v71, v53
	s_nop 0
	v_max3_f32 v48, v48, v74, v54
	v_max3_f32 v47, v47, v70, v51
	s_nop 0
	v_cndmask_b32_e32 v37, v210, v64, vcc
	v_max3_f32 v48, v48, v73, v52
	v_max3_f32 v47, v47, v69, v50
	s_nop 0
	v_max3_f32 v48, v48, v57, v41
	v_max3_f32 v47, v47, v55, v38
	s_nop 0
	v_max3_f32 v48, v48, v56, v40
	v_max3_f32 v47, v47, v45, v36
	s_nop 0
	v_max3_f32 v48, v48, v46, v39
	v_max3_f32 v47, v47, v43, v35
	s_nop 0
	v_max3_f32 v48, v48, v44, v37
	v_max3_f32 v47, v47, v42, v34
	s_nop 0
	v_max_f32_e32 v47, v47, v47
	v_max_f32_e32 v48, v48, v48
	v_max_f32_e32 v47, v48, v47
	v_mov_b32_e32 v48, v47
	s_nop 1
	v_permlane32_swap_b32_e32 v48, v47
	s_waitcnt lgkmcnt(0)
	v_max_f32_e32 v47, v47, v48
	v_cmp_lt_f32_e64 s[26:27], s2, v47
	s_mov_b32 s2, 0x41000000
	v_cmp_lt_f32_e32 vcc, s2, v47
	s_mov_b32 s2, 0xc1000000
	v_cmp_gt_f32_e64 s[2:3], s2, v47
	s_and_b64 s[2:3], s[2:3], s[26:27]
	s_andn2_b64 s[2:3], s[2:3], s[22:23]
	s_or_b64 s[2:3], s[2:3], vcc
	s_and_b64 vcc, exec, s[2:3]
	s_cbranch_vccnz .LBB0_515

; #define LAS __attribute__((address_space(3)))
; #define MFMA32(a, b, c) __builtin_amdgcn_mfma_f32_32x32x16_bf16((a), (b), (c), 0, 0, 0)
; DI void qk_acc(lptr Kt, const bf16x8 (&qf)[4], f32x16& s0, f32x16& s1, int lane) {
;     const int i = lane & 31, hi = lane >> 5;
;     const int krow = (i & 19) | ((i & 4) << 1) | ((i & 8) >> 1);
;     lptr kp = Kt + krow * KPB + hi * 16;
;     bf16x8 a0[4], a1[4];
; #pragma unroll
;     for (int d0 = 0; d0 < 4; ++d0) { a0[d0] = *(LAS bf16x8*)(kp + d0 * 32); a1[d0] = *(LAS bf16x8*)(kp + 32 * KPB + d0 * 32); }
;     __builtin_amdgcn_s_setprio(1);
; #pragma unroll
;     for (int d0 = 0; d0 < 4; ++d0) { s0 = MFMA32(a0[d0], qf[d0], s0); s1 = MFMA32(a1[d0], qf[d0], s1); }
;     __builtin_amdgcn_s_setprio(0);
; template <int MODE>
; DI void bias_init(f32x16& s0, f32x16& s1, const TP& tp, float fbm, int hi) {
; #pragma unroll
;     for (int r = 0; r < 16; ++r) {
;         const int kvc = 16 * (r >> 3) + (r & 7);
;         if (MODE == 0) { s0[r] = __builtin_fmaf(-L2E, tp.cs[kvc + 8 * hi], fbm); s1[r] = __builtin_fmaf(-L2E, tp.cs[kvc + 32 + 8 * hi], fbm); }
;         else { s0[r] = __builtin_fmaf(tp.sl, (float)kvc, fbm); s1[r] = __builtin_fmaf(tp.sl, (float)(kvc + 32), fbm); }
;     }
; }
; DI float max3_asm(float a, float b, float c) { float r; asm("v_max3_f32 %0, %1, %2, %3" : "=v"(r) : "v"(a), "v"(b), "v"(c)); return r; }
; template <bool MASK>
; DI float mask_rowmax(f32x16& s0, f32x16& s1, const TP& tp) {
;     if (MASK) {
; #pragma unroll
;         for (int r = 0; r < 16; ++r) {
;             const int kvc = 16 * (r >> 3) + (r & 7);
;             const bool v0 = tp.sel && (kvc <= tp.lim) && (kvc > tp.lim2), v1 = tp.sel && (kvc + 32 <= tp.lim) && (kvc + 32 > tp.lim2);
;             s0[r] = v0 ? s0[r] : -1e30f; s1[r] = v1 ? s1[r] : -1e30f;
;         }
;     }
;     const float seed = __builtin_fminf(s0[15], s1[15]);
;     float ma = seed, mb = seed;
; #pragma unroll
;     for (int r = 0; r < 16; r += 2) { ma = max3_asm(ma, s0[r], s1[r]); mb = max3_asm(mb, s0[r + 1], s1[r + 1]); }
;     const float mx = fmaxf(ma, mb);
;     return fmaxf(mx, __shfl_xor(mx, 32));
; }
.LBB0_535:
	s_and_b64 vcc, exec, s[2:3]
	s_cbranch_vccz .LBB0_531
	v_sub_f32_e32 v18, v50, v49
	v_add3_u32 v232, s52, v131, v133
	ds_read_b128 v[50:53], v232 offset:4608
	ds_read_b128 v[54:57], v232
	ds_read_b128 v[58:61], v232 offset:32
	ds_read_b128 v[62:65], v232 offset:4640
	ds_read_b128 v[66:69], v232 offset:64
	ds_read_b128 v[70:73], v232 offset:4672
	ds_read_b128 v[88:91], v232 offset:96
	ds_read_b128 v[92:95], v232 offset:4704
	s_mov_b32 s2, 2.0
	v_mov_b32_e32 v79, v78
	s_mov_b32 s3, 0x40400000
	v_pk_fma_f32 v[32:33], v[78:79], s[4:5], v[18:19] op_sel_hi:[1,1,0]
	v_pk_fma_f32 v[30:31], v[78:79], s[14:15], v[18:19] op_sel_hi:[1,1,0]
	v_pk_fma_f32 v[28:29], v[78:79], s[16:17], v[18:19] op_sel_hi:[1,1,0]
	v_pk_fma_f32 v[26:27], v[78:79], s[94:95], v[18:19] op_sel_hi:[1,1,0]
	v_pk_fma_f32 v[24:25], v[78:79], s[96:97], v[18:19] op_sel_hi:[1,1,0]
	v_pk_fma_f32 v[22:23], v[78:79], s[84:85], v[18:19] op_sel_hi:[1,1,0]
	v_pk_fma_f32 v[20:21], v[78:79], s[72:73], v[18:19] op_sel_hi:[1,1,0]
	v_pk_fma_f32 v[4:5], v[80:81], s[2:3], v[18:19] op_sel_hi:[1,1,0]
	s_mov_b32 s2, 4.0
	s_mov_b32 s3, 0x40a00000
	v_pk_fma_f32 v[6:7], v[80:81], s[2:3], v[18:19] op_sel_hi:[1,1,0]
	s_mov_b32 s2, 0x40c00000
	s_mov_b32 s3, 0x40e00000
	v_pk_fma_f32 v[8:9], v[80:81], s[2:3], v[18:19] op_sel_hi:[1,1,0]
	s_mov_b32 s2, 0x41800000
	s_mov_b32 s3, 0x41880000
	v_pk_fma_f32 v[10:11], v[80:81], s[2:3], v[18:19] op_sel_hi:[1,1,0]
	s_mov_b32 s2, 0x41900000
	s_mov_b32 s3, 0x41980000
	v_pk_fma_f32 v[12:13], v[80:81], s[2:3], v[18:19] op_sel_hi:[1,1,0]
	s_mov_b32 s2, 0x41a00000
	s_mov_b32 s3, 0x41a80000
	v_fma_f32 v2, 0, v78, v18
	v_add_f32_e32 v3, v78, v18
	v_pk_fma_f32 v[14:15], v[80:81], s[2:3], v[18:19] op_sel_hi:[1,1,0]
	v_pk_fma_f32 v[16:17], v[80:81], s[18:19], v[18:19] op_sel_hi:[1,1,0]
	v_pk_fma_f32 v[18:19], v[82:83], s[44:45], v[18:19] op_sel_hi:[1,1,0]
	s_setprio 1
	s_waitcnt vmcnt(4) lgkmcnt(6)
	v_mfma_f32_32x32x16_bf16 v[2:17], v[54:57], v[98:101], v[2:17]
	v_mfma_f32_32x32x16_bf16 v[18:33], v[50:53], v[98:101], v[18:33]
	s_waitcnt vmcnt(3) lgkmcnt(5)
	v_mfma_f32_32x32x16_bf16 v[2:17], v[58:61], v[102:105], v[2:17]
	s_waitcnt lgkmcnt(4)
	v_mfma_f32_32x32x16_bf16 v[18:33], v[62:65], v[102:105], v[18:33]
	s_waitcnt vmcnt(2) lgkmcnt(3)
	v_mfma_f32_32x32x16_bf16 v[2:17], v[66:69], v[106:109], v[2:17]
	s_waitcnt lgkmcnt(2)
	v_mfma_f32_32x32x16_bf16 v[18:33], v[70:73], v[106:109], v[18:33]
	s_waitcnt vmcnt(1) lgkmcnt(1)
	v_mfma_f32_32x32x16_bf16 v[2:17], v[88:91], v[110:113], v[2:17]
	s_waitcnt lgkmcnt(0)
	v_mfma_f32_32x32x16_bf16 v[18:33], v[92:95], v[110:113], v[18:33]
	s_setprio 0
	v_cmp_lt_i32_e32 vcc, 0, v48
	s_mov_b32 s2, 0xefa18f08
	s_nop 6
	v_cndmask_b32_e32 v51, v210, v3, vcc
	v_cmp_lt_i32_e64 s[98:99], -1, v48
	v_cmp_lt_i32_e64 s[100:101], 32, v48
	v_cmp_lt_i32_e32 vcc, 31, v48
	v_cndmask_b32_e64 v55, v210, v2, s[98:99]
	v_cndmask_b32_e64 v53, v210, v19, s[100:101]
	v_cndmask_b32_e32 v58, v210, v18, vcc
	v_cmp_lt_i32_e64 s[98:99], 2, v48
	v_cmp_lt_i32_e64 s[100:101], 1, v48
	v_cmp_lt_i32_e32 vcc, 34, v48
	v_cndmask_b32_e64 v50, v210, v5, s[98:99]
	v_cndmask_b32_e64 v57, v210, v4, s[100:101]
	v_cndmask_b32_e32 v21, v210, v21, vcc
	v_cmp_lt_i32_e64 s[98:99], 33, v48
	v_cmp_lt_i32_e64 s[100:101], 4, v48
	v_cmp_lt_i32_e32 vcc, 3, v48
	v_cndmask_b32_e64 v59, v210, v20, s[98:99]
	v_cndmask_b32_e64 v18, v210, v7, s[100:101]
	v_cndmask_b32_e32 v54, v210, v6, vcc
	v_cmp_lt_i32_e64 s[98:99], 36, v48
	v_cmp_lt_i32_e64 s[100:101], 35, v48
	v_cmp_lt_i32_e32 vcc, 6, v48
	v_cndmask_b32_e64 v20, v210, v23, s[98:99]
	v_cndmask_b32_e64 v56, v210, v22, s[100:101]
	v_cndmask_b32_e32 v9, v210, v9, vcc
	v_cmp_lt_i32_e64 s[98:99], 5, v48
	v_cmp_lt_i32_e64 s[100:101], 38, v48
	v_cmp_lt_i32_e32 vcc, 37, v48
	v_cndmask_b32_e64 v52, v210, v8, s[98:99]
	v_cndmask_b32_e64 v19, v210, v25, s[100:101]
	v_cndmask_b32_e32 v25, v210, v24, vcc
	v_cmp_lt_i32_e64 s[98:99], 16, v48
	v_cmp_lt_i32_e64 s[100:101], 15, v48
	v_cmp_lt_i32_e32 vcc, 48, v48
	v_cndmask_b32_e64 v6, v210, v11, s[98:99]
	v_cndmask_b32_e64 v22, v210, v10, s[100:101]
	v_cndmask_b32_e32 v8, v210, v27, vcc
	v_cmp_lt_i32_e32 vcc, 47, v48
	s_nop 1
	v_cndmask_b32_e32 v24, v210, v26, vcc
	v_cmp_lt_i32_e32 vcc, 18, v48
	v_and_b32_e32 v26, 64, v209
	v_add_u32_e32 v26, 64, v26
	v_cndmask_b32_e32 v4, v210, v13, vcc
	v_cmp_lt_i32_e64 s[98:99], 17, v48
	v_cmp_lt_i32_e64 s[100:101], 50, v48
	v_cmp_lt_i32_e32 vcc, 49, v48
	v_cndmask_b32_e64 v13, v210, v12, s[98:99]
	v_cndmask_b32_e64 v7, v210, v29, s[100:101]
	v_cndmask_b32_e32 v23, v210, v28, vcc
	v_cmp_lt_i32_e64 s[98:99], 20, v48
	v_cmp_lt_i32_e64 s[100:101], 19, v48
	v_cmp_lt_i32_e32 vcc, 52, v48
	v_cndmask_b32_e64 v3, v210, v15, s[98:99]
	v_cndmask_b32_e64 v11, v210, v14, s[100:101]
	v_cndmask_b32_e32 v5, v210, v31, vcc
	v_cmp_lt_i32_e64 s[98:99], 51, v48
	v_cmp_lt_i32_e64 s[100:101], 22, v48
	v_cmp_lt_i32_e32 vcc, 21, v48
	v_cndmask_b32_e64 v14, v210, v30, s[98:99]
	v_cndmask_b32_e64 v2, v210, v17, s[100:101]
	v_cndmask_b32_e32 v10, v210, v16, vcc
	v_cmp_lt_i32_e32 vcc, 54, v48
	v_max_f32_e32 v16, v2, v2
	s_nop 0
	v_cndmask_b32_e32 v17, v210, v33, vcc
	v_max_f32_e32 v15, v17, v17
	v_min_f32_e32 v15, v16, v15
	v_max3_f32 v16, v15, v55, v58
	v_max3_f32 v15, v15, v51, v53
	v_cmp_lt_i32_e32 vcc, 53, v48
	v_max3_f32 v16, v16, v57, v59
	v_max3_f32 v15, v15, v50, v21
	s_nop 0
	v_max3_f32 v16, v16, v54, v56
	v_max3_f32 v15, v15, v18, v20
	s_nop 0
	v_cndmask_b32_e32 v12, v210, v32, vcc
	v_max3_f32 v16, v16, v52, v25
	v_max3_f32 v15, v15, v9, v19
	s_nop 0
	v_max3_f32 v16, v16, v22, v24
	v_max3_f32 v15, v15, v6, v8
	s_nop 0
	v_max3_f32 v16, v16, v13, v23
	v_max3_f32 v15, v15, v4, v7
	s_nop 0
	v_max3_f32 v16, v16, v11, v14
	v_max3_f32 v15, v15, v3, v5
	s_nop 0
	v_max3_f32 v16, v16, v10, v12
	v_max3_f32 v15, v15, v2, v17
	s_nop 0
	v_max_f32_e32 v15, v15, v15
	v_max_f32_e32 v16, v16, v16
	v_max_f32_e32 v15, v16, v15
	v_mov_b32_e32 v16, v15
	s_nop 1
	v_permlane32_swap_b32_e32 v16, v15
	s_waitcnt lgkmcnt(0)
	v_max_f32_e32 v15, v15, v16
	v_cmp_lt_f32_e64 s[24:25], s2, v15
	s_mov_b32 s2, 0x41000000
	v_cmp_lt_f32_e32 vcc, s2, v15
	s_mov_b32 s2, 0xc1000000
	v_cmp_gt_f32_e64 s[2:3], s2, v15
	s_and_b64 s[2:3], s[2:3], s[24:25]
	s_andn2_b64 s[2:3], s[2:3], s[0:1]
	s_or_b64 s[2:3], s[2:3], vcc
	s_and_b64 vcc, exec, s[2:3]
	s_cbranch_vccnz .LBB0_541

; template <int MODE>
; DI void bias_init(f32x16& s0, f32x16& s1, const TP& tp, float fbm, int hi) {
; #pragma unroll
;     for (int r = 0; r < 16; ++r) {
;         const int kvc = 16 * (r >> 3) + (r & 7);
;         if (MODE == 0) { s0[r] = __builtin_fmaf(-L2E, tp.cs[kvc + 8 * hi], fbm); s1[r] = __builtin_fmaf(-L2E, tp.cs[kvc + 32 + 8 * hi], fbm); }
;         else { s0[r] = __builtin_fmaf(tp.sl, (float)kvc, fbm); s1[r] = __builtin_fmaf(tp.sl, (float)(kvc + 32), fbm); }
;     }
; }
; DI float max3_asm(float a, float b, float c) { float r; asm("v_max3_f32 %0, %1, %2, %3" : "=v"(r) : "v"(a), "v"(b), "v"(c)); return r; }
; template <bool MASK>
; DI float mask_rowmax(f32x16& s0, f32x16& s1, const TP& tp) {
;     if (MASK) {
; #pragma unroll
;         for (int r = 0; r < 16; ++r) {
;             const int kvc = 16 * (r >> 3) + (r & 7);
;             const bool v0 = tp.sel && (kvc <= tp.lim) && (kvc > tp.lim2), v1 = tp.sel && (kvc + 32 <= tp.lim) && (kvc + 32 > tp.lim2);
;             s0[r] = v0 ? s0[r] : -1e30f; s1[r] = v1 ? s1[r] : -1e30f;
; DI void cmpwin_unit(const Params& P, lptr L, int u, int tid, int lane, int wid) {
;     ...
;             const int n0 = jt * 64;
;             TP tp; tp.cs = nullptr; tp.sl = 16.f * sl; tp.fb = sl * (float)(16 * (n0 + 8 * hi) + 31 - t); tp.lim = nlim - n0 - 8 * hi; tp.lim2 = -(1 << 30); tp.sel = true;
;             f32x16 s0, s1;
;             bias_init<1>(s0, s1, tp, tp.fb - mfin, hi);
;             qk_acc(Kt, qf, s0, s1, lane);
;             if (n0 + 63 > nfull) (void)mask_rowmax<true>(s0, s1, tp);
.LBB0_548:
	s_and_b32 s25, s24, 1
	s_mul_i32 s26, s25, 0x2400
	v_add_u32_e32 v232, s26, v170
	ds_read_b128 v[90:93], v232 offset:4608
	ds_read_b128 v[94:97], v232
	ds_read_b128 v[114:117], v232 offset:32
	ds_read_b128 v[118:121], v232 offset:4640
	ds_read_b128 v[154:157], v232 offset:64
	ds_read_b128 v[158:161], v232 offset:4672
	ds_read_b128 v[162:165], v232 offset:96
	ds_read_b128 v[166:169], v232 offset:4704
	s_lshl_b32 s2, s24, 6
	v_or_b32_e32 v88, s2, v126
	v_lshlrev_b32_e32 v34, 4, v88
	v_sub_u32_e32 v34, v34, v85
	v_add_u32_e32 v34, 31, v34
	v_cvt_f32_i32_e32 v34, v34
	s_mov_b32 s22, 2.0
	v_fma_f32 v50, v150, v34, -v87
	v_mov_b32_e32 v79, v78
	s_mov_b32 s23, 0x40400000
	v_pk_fma_f32 v[64:65], v[78:79], s[4:5], v[50:51] op_sel_hi:[1,1,0]
	v_pk_fma_f32 v[62:63], v[78:79], s[14:15], v[50:51] op_sel_hi:[1,1,0]
	v_pk_fma_f32 v[60:61], v[78:79], s[16:17], v[50:51] op_sel_hi:[1,1,0]
	v_pk_fma_f32 v[58:59], v[78:79], s[94:95], v[50:51] op_sel_hi:[1,1,0]
	v_pk_fma_f32 v[56:57], v[78:79], s[96:97], v[50:51] op_sel_hi:[1,1,0]
	v_pk_fma_f32 v[54:55], v[78:79], s[84:85], v[50:51] op_sel_hi:[1,1,0]
	v_pk_fma_f32 v[52:53], v[78:79], s[72:73], v[50:51] op_sel_hi:[1,1,0]
	v_pk_fma_f32 v[36:37], v[80:81], s[22:23], v[50:51] op_sel_hi:[1,1,0]
	s_mov_b32 s22, 4.0
	s_mov_b32 s23, 0x40a00000
	v_pk_fma_f32 v[38:39], v[80:81], s[22:23], v[50:51] op_sel_hi:[1,1,0]
	s_mov_b32 s22, 0x40c00000
	s_mov_b32 s23, 0x40e00000
	v_pk_fma_f32 v[40:41], v[80:81], s[22:23], v[50:51] op_sel_hi:[1,1,0]
	s_mov_b32 s22, 0x41800000
	s_mov_b32 s23, 0x41880000
	v_pk_fma_f32 v[42:43], v[80:81], s[22:23], v[50:51] op_sel_hi:[1,1,0]
	s_mov_b32 s22, 0x41900000
	s_mov_b32 s23, 0x41980000
	v_pk_fma_f32 v[44:45], v[80:81], s[22:23], v[50:51] op_sel_hi:[1,1,0]
	s_mov_b32 s22, 0x41a00000
	s_mov_b32 s23, 0x41a80000
	v_fma_f32 v34, 0, v78, v50
	v_add_f32_e32 v35, v78, v50
	v_pk_fma_f32 v[46:47], v[80:81], s[22:23], v[50:51] op_sel_hi:[1,1,0]
	v_pk_fma_f32 v[48:49], v[80:81], s[18:19], v[50:51] op_sel_hi:[1,1,0]
	v_pk_fma_f32 v[50:51], v[82:83], s[44:45], v[50:51] op_sel_hi:[1,1,0]
	s_setprio 1
	s_waitcnt lgkmcnt(6)
	v_mfma_f32_32x32x16_bf16 v[34:49], v[94:97], v[98:101], v[34:49]
	v_mfma_f32_32x32x16_bf16 v[50:65], v[90:93], v[98:101], v[50:65]
	s_waitcnt lgkmcnt(5)
	v_mfma_f32_32x32x16_bf16 v[34:49], v[114:117], v[102:105], v[34:49]
	s_waitcnt lgkmcnt(4)
	v_mfma_f32_32x32x16_bf16 v[50:65], v[118:121], v[102:105], v[50:65]
	s_waitcnt lgkmcnt(3)
	v_mfma_f32_32x32x16_bf16 v[34:49], v[154:157], v[106:109], v[34:49]
	s_waitcnt lgkmcnt(2)
	v_mfma_f32_32x32x16_bf16 v[50:65], v[158:161], v[106:109], v[50:65]
	s_waitcnt lgkmcnt(1)
	v_mfma_f32_32x32x16_bf16 v[34:49], v[162:165], v[110:113], v[34:49]
	s_waitcnt lgkmcnt(0)
	v_mfma_f32_32x32x16_bf16 v[50:65], v[166:169], v[110:113], v[50:65]
	s_setprio 0
	s_or_b32 s3, s2, 63
	s_cmp_le_i32 s3, s29
	s_cbranch_scc1 .LBB0_550
	v_sub_u32_e32 v79, v86, v88
	v_cmp_lt_i32_e32 vcc, -1, v79
	s_nop 3
	v_cndmask_b32_e32 v34, v210, v34, vcc
	v_cmp_lt_i32_e64 s[98:99], 31, v79
	v_cmp_lt_i32_e64 s[100:101], 0, v79
	v_cmp_lt_i32_e32 vcc, 32, v79
	v_cndmask_b32_e64 v50, v210, v50, s[98:99]
	v_cndmask_b32_e64 v35, v210, v35, s[100:101]
	v_cndmask_b32_e32 v51, v210, v51, vcc
	v_cmp_lt_i32_e64 s[98:99], 1, v79
	v_cmp_lt_i32_e64 s[100:101], 33, v79
	v_cmp_lt_i32_e32 vcc, 2, v79
	v_cndmask_b32_e64 v36, v210, v36, s[98:99]
	v_cndmask_b32_e64 v52, v210, v52, s[100:101]
	v_cndmask_b32_e32 v37, v210, v37, vcc
	v_cmp_lt_i32_e64 s[98:99], 34, v79
	v_cmp_lt_i32_e64 s[100:101], 3, v79
	v_cmp_lt_i32_e32 vcc, 35, v79
	v_cndmask_b32_e64 v53, v210, v53, s[98:99]
	v_cndmask_b32_e64 v38, v210, v38, s[100:101]
	v_cndmask_b32_e32 v54, v210, v54, vcc
	v_cmp_lt_i32_e64 s[98:99], 4, v79
	v_cmp_lt_i32_e64 s[100:101], 36, v79
	v_cmp_lt_i32_e32 vcc, 5, v79
	v_cndmask_b32_e64 v39, v210, v39, s[98:99]
	v_cndmask_b32_e64 v55, v210, v55, s[100:101]
	v_cndmask_b32_e32 v40, v210, v40, vcc
	v_cmp_lt_i32_e64 s[98:99], 37, v79
	v_cmp_lt_i32_e64 s[100:101], 6, v79
	v_cmp_lt_i32_e32 vcc, 38, v79
	v_cndmask_b32_e64 v56, v210, v56, s[98:99]
	v_cndmask_b32_e64 v41, v210, v41, s[100:101]
	v_cndmask_b32_e32 v57, v210, v57, vcc
	v_cmp_lt_i32_e64 s[98:99], 15, v79
	v_cmp_lt_i32_e64 s[100:101], 47, v79
	v_cmp_lt_i32_e32 vcc, 16, v79
	v_cndmask_b32_e64 v42, v210, v42, s[98:99]
	v_cndmask_b32_e64 v58, v210, v58, s[100:101]
	v_cndmask_b32_e32 v43, v210, v43, vcc
	v_cmp_lt_i32_e64 s[98:99], 48, v79
	v_cmp_lt_i32_e64 s[100:101], 17, v79
	v_cmp_lt_i32_e32 vcc, 49, v79
	v_cndmask_b32_e64 v59, v210, v59, s[98:99]
	v_cndmask_b32_e64 v44, v210, v44, s[100:101]
	v_cndmask_b32_e32 v60, v210, v60, vcc
	v_cmp_lt_i32_e64 s[98:99], 18, v79
	v_cmp_lt_i32_e64 s[100:101], 50, v79
	v_cmp_lt_i32_e32 vcc, 19, v79
	v_cndmask_b32_e64 v45, v210, v45, s[98:99]
	v_cndmask_b32_e64 v61, v210, v61, s[100:101]
	v_cndmask_b32_e32 v46, v210, v46, vcc
	v_cmp_lt_i32_e64 s[98:99], 51, v79
	v_cmp_lt_i32_e64 s[100:101], 20, v79
	v_cmp_lt_i32_e32 vcc, 52, v79
	v_cndmask_b32_e64 v62, v210, v62, s[98:99]
	v_cndmask_b32_e64 v47, v210, v47, s[100:101]
	v_cndmask_b32_e32 v63, v210, v63, vcc
	v_cmp_lt_i32_e64 s[98:99], 21, v79
	v_cmp_lt_i32_e64 s[100:101], 53, v79
	v_cmp_lt_i32_e32 vcc, 22, v79
	v_cndmask_b32_e64 v48, v210, v48, s[98:99]
	v_cndmask_b32_e64 v64, v210, v64, s[100:101]
	v_cndmask_b32_e32 v49, v210, v49, vcc
	v_cmp_lt_i32_e32 vcc, 54, v79
	s_nop 1
	v_cndmask_b32_e32 v65, v210, v65, vcc
